# lever 4 (one static priority raise for the second-dispatched wave half) applied to the NA attention phase: waves 4-7 run at s_setprio 1 for the whole phase
# baseline (speedup 1.0000x reference)
.LBB0_330:
	s_and_b64 vcc, exec, s[2:3]
	s_cbranch_vccz .LBB0_423
	v_readlane_b32 s2, v252, 62
	v_readlane_b32 s40, v254, 55
	v_readlane_b32 s46, v254, 61
	v_add_u32_e32 v0, s2, v125
	v_readlane_b32 s2, v252, 63
	v_readlane_b32 s47, v254, 62
	s_waitcnt vmcnt(0)
	v_add_u32_e32 v131, 0x9000, v222
	v_add_u32_e32 v115, s2, v0
	v_lshlrev_b32_e32 v0, 1, v0
	v_and_b32_e32 v127, 62, v0
	v_sub_u32_e64 v0, v127, 4 clamp
	v_bfe_u32 v2, v115, 5, 4
	v_min_u32_e32 v128, 56, v0
	v_lshlrev_b32_e32 v0, 7, v2
	v_lshlrev_b32_e32 v129, 6, v128
	v_lshlrev_b32_e32 v114, 6, v2
	v_lshl_add_u64 v[116:117], s[26:27], 0, v[0:1]
	v_mul_u32_u24_e32 v130, 0x1d1, v2
	v_lshl_add_u64 v[118:119], s[46:47], 0, v[0:1]
	v_sub_u32_e32 v132, v128, v127
	v_or_b32_e32 v133, 1, v128
	s_mov_b32 s34, 0
	v_readlane_b32 s41, v254, 56
	v_readlane_b32 s42, v254, 57
	v_readlane_b32 s43, v254, 58
	v_readlane_b32 s44, v254, 59
	v_readlane_b32 s45, v254, 60
	v_readlane_b32 s48, v254, 63
	v_readlane_b32 s49, v255, 0
	v_readlane_b32 s50, v255, 1
	v_readlane_b32 s51, v255, 2
	v_readlane_b32 s52, v255, 3
	v_readlane_b32 s53, v255, 4
	v_readlane_b32 s54, v255, 5
	v_readlane_b32 s55, v255, 6
	v_readfirstlane_b32 s100, v163
	s_bitcmp1_b32 s100, 8
	s_cbranch_scc0 .Lna_prio_done
	s_setprio 1
.Lna_prio_done:
	s_branch .LBB0_333
.LBB0_332:
	v_fma_f32 v0, v70, s17, -v144
	v_exp_f32_e32 v0, v0
	v_fma_f32 v44, v71, s17, -v144
	v_exp_f32_e32 v44, v44
	v_fma_f32 v45, v72, s17, -v144
	v_exp_f32_e32 v45, v45
	v_fma_f32 v46, v73, s17, -v144
	v_exp_f32_e32 v46, v46
	v_add_f32_e32 v47, 0, v0
	v_add_f32_e32 v47, v44, v47
	v_add_f32_e32 v47, v45, v47
	v_cvt_pk_bf16_f32 v44, v0, v44
	v_fma_f32 v0, v66, s17, -v144
	v_add_f32_e32 v47, v46, v47
	v_cvt_pk_bf16_f32 v45, v45, v46
	v_exp_f32_e32 v0, v0
	v_fma_f32 v46, v67, s17, -v144
	v_exp_f32_e32 v46, v46
	v_fma_f32 v48, v68, s17, -v144
	v_exp_f32_e32 v48, v48
	v_fma_f32 v49, v69, s17, -v144
	v_exp_f32_e32 v49, v49
	v_add_f32_e32 v47, v0, v47
	v_add_f32_e32 v47, v46, v47
	v_add_f32_e32 v47, v48, v47
	v_cvt_pk_bf16_f32 v46, v0, v46
	v_fma_f32 v0, v62, s17, -v144
	v_add_f32_e32 v66, v49, v47
	v_cvt_pk_bf16_f32 v47, v48, v49
	v_exp_f32_e32 v0, v0
	v_fma_f32 v48, v63, s17, -v144
	v_exp_f32_e32 v48, v48
	v_fma_f32 v49, v64, s17, -v144
	v_exp_f32_e32 v49, v49
	v_fma_f32 v62, v65, s17, -v144
	v_exp_f32_e32 v63, v62
	v_add_f32_e32 v62, v0, v66
	v_add_f32_e32 v62, v48, v62
	v_add_f32_e32 v62, v49, v62
	v_add_f32_e32 v64, v63, v62
	v_cvt_pk_bf16_f32 v62, v0, v48
	v_fma_f32 v0, v38, s17, -v144
	v_exp_f32_e32 v0, v0
	v_fma_f32 v38, v39, s17, -v144
	v_exp_f32_e32 v38, v38
	v_fma_f32 v39, v40, s17, -v144
	v_exp_f32_e32 v39, v39
	v_fma_f32 v40, v41, s17, -v144
	v_exp_f32_e32 v40, v40
	v_add_f32_e32 v41, v0, v64
	v_add_f32_e32 v41, v38, v41
	v_add_f32_e32 v41, v39, v41
	v_cvt_pk_bf16_f32 v64, v0, v38
	v_fma_f32 v38, v58, s17, -v142
	v_add_f32_e32 v41, v40, v41
	v_cvt_pk_bf16_f32 v65, v39, v40
	v_exp_f32_e32 v38, v38
	v_fma_f32 v39, v59, s17, -v142
	v_add_f32_e32 v0, v140, v41
	v_exp_f32_e32 v39, v39
	v_fma_f32 v40, v60, s17, -v142
	v_fma_f32 v41, v61, s17, -v142
	v_exp_f32_e32 v40, v40
	v_exp_f32_e32 v41, v41
	v_add_f32_e32 v48, 0, v38
	v_add_f32_e32 v48, v39, v48
	v_add_f32_e32 v48, v40, v48
	v_cvt_pk_bf16_f32 v38, v38, v39
	v_cvt_pk_bf16_f32 v39, v40, v41
	v_fma_f32 v40, v54, s17, -v142
	v_add_f32_e32 v48, v41, v48
	v_exp_f32_e32 v40, v40
	v_fma_f32 v41, v55, s17, -v142
	v_cvt_pk_bf16_f32 v63, v49, v63
	v_exp_f32_e32 v41, v41
	v_fma_f32 v49, v56, s17, -v142
	v_fma_f32 v54, v57, s17, -v142
	v_exp_f32_e32 v49, v49
	v_exp_f32_e32 v54, v54
	v_add_f32_e32 v48, v40, v48
	v_add_f32_e32 v48, v41, v48
	v_add_f32_e32 v48, v49, v48
	v_cvt_pk_bf16_f32 v40, v40, v41
	v_cvt_pk_bf16_f32 v41, v49, v54
	v_fma_f32 v49, v50, s17, -v142
	v_exp_f32_e32 v49, v49
	v_fma_f32 v50, v51, s17, -v142
	v_exp_f32_e32 v50, v50
	v_fma_f32 v51, v52, s17, -v142
	v_exp_f32_e32 v51, v51
	v_fma_f32 v52, v53, s17, -v142
	v_add_f32_e32 v48, v54, v48
	v_exp_f32_e32 v52, v52
	v_add_f32_e32 v48, v49, v48
	v_add_f32_e32 v48, v50, v48
	v_add_f32_e32 v48, v51, v48
	v_fma_f32 v34, v34, s17, -v142
	v_add_f32_e32 v53, v52, v48
	v_cvt_pk_bf16_f32 v48, v49, v50
	v_exp_f32_e32 v50, v34
	v_fma_f32 v34, v35, s17, -v142
	v_exp_f32_e32 v60, v34
	v_fma_f32 v34, v36, s17, -v142
	v_exp_f32_e32 v61, v34
	v_add_f32_e32 v34, v50, v53
	v_add_f32_e32 v34, v60, v34
	v_cvt_pk_bf16_f32 v49, v51, v52
	v_add_f32_e32 v51, v61, v34
	v_fma_f32 v34, v37, s17, -v142
	v_exp_f32_e32 v70, v34
	v_mul_u32_u24_e32 v34, 0x48, v135
	v_lshl_add_u32 v71, v34, 1, v136
	ds_read_b64_tr_b16 v[36:37], v71 offset:20736
	ds_read_b64_tr_b16 v[34:35], v71 offset:18432
	ds_read_b64_tr_b16 v[54:55], v71 offset:20768
	ds_read_b64_tr_b16 v[52:53], v71 offset:18464
	ds_read_b64_tr_b16 v[56:57], v71 offset:23040
	ds_read_b64_tr_b16 v[58:59], v71 offset:25344
	ds_read_b64_tr_b16 v[68:69], v71 offset:25376
	ds_read_b64_tr_b16 v[66:67], v71 offset:23072
	v_add_f32_e32 v72, v70, v51
	v_cvt_pk_bf16_f32 v50, v50, v60
	v_cvt_pk_bf16_f32 v51, v61, v70
	v_add_f32_e32 v60, v137, v72
	s_waitcnt lgkmcnt(6)
	v_mfma_f32_16x16x32_bf16 v[18:21], v[34:37], v[44:47], v[18:21]
	v_mfma_f32_16x16x32_bf16 v[30:33], v[34:37], v[38:41], v[30:33]
	s_waitcnt lgkmcnt(4)
	v_mfma_f32_16x16x32_bf16 v[22:25], v[52:55], v[44:47], v[22:25]
	v_mfma_f32_16x16x32_bf16 v[26:29], v[52:55], v[38:41], v[26:29]
	s_waitcnt lgkmcnt(2)
	v_mfma_f32_16x16x32_bf16 v[18:21], v[56:59], v[62:65], v[18:21]
	v_mfma_f32_16x16x32_bf16 v[30:33], v[56:59], v[48:51], v[30:33]
	s_waitcnt lgkmcnt(0)
	v_mfma_f32_16x16x32_bf16 v[22:25], v[66:69], v[62:65], v[22:25]
	v_mfma_f32_16x16x32_bf16 v[26:29], v[66:69], v[48:51], v[26:29]
	ds_read_b64_tr_b16 v[36:37], v71 offset:20800
	ds_read_b64_tr_b16 v[34:35], v71 offset:18496
	ds_read_b64_tr_b16 v[54:55], v71 offset:20832
	ds_read_b64_tr_b16 v[52:53], v71 offset:18528
	ds_read_b64_tr_b16 v[56:57], v71 offset:23104
	ds_read_b64_tr_b16 v[58:59], v71 offset:25408
	ds_read_b64_tr_b16 v[68:69], v71 offset:25440
	ds_read_b64_tr_b16 v[66:67], v71 offset:23136
	s_waitcnt lgkmcnt(6)
	v_mfma_f32_16x16x32_bf16 v[10:13], v[34:37], v[44:47], v[10:13]
	v_mfma_f32_16x16x32_bf16 v[14:17], v[34:37], v[38:41], v[14:17]
	s_waitcnt lgkmcnt(4)
	v_mfma_f32_16x16x32_bf16 v[2:5], v[52:55], v[44:47], v[2:5]
	v_mfma_f32_16x16x32_bf16 v[6:9], v[52:55], v[38:41], v[6:9]
	s_waitcnt lgkmcnt(2)
	v_mfma_f32_16x16x32_bf16 v[10:13], v[56:59], v[62:65], v[10:13]
	v_mfma_f32_16x16x32_bf16 v[14:17], v[56:59], v[48:51], v[14:17]
	s_waitcnt lgkmcnt(0)
	v_mfma_f32_16x16x32_bf16 v[2:5], v[66:69], v[62:65], v[2:5]
	v_mfma_f32_16x16x32_bf16 v[6:9], v[66:69], v[48:51], v[6:9]
	v_mov_b32_e32 v34, v0
	s_nop 1
	v_permlane16_swap_b32_e32 v34, v0
	s_barrier
	s_add_i32 s34, s34, 1
	v_add_f32_e32 v0, v0, v34
	v_mov_b32_e32 v34, v0
	s_nop 1
	v_permlane32_swap_b32_e32 v34, v0
	s_cmp_eq_u32 s34, 8
	v_add_f32_e32 v0, v0, v34
	v_div_scale_f32 v36, s[2:3], v0, v0, 1.0
	v_rcp_f32_e32 v37, v36
	v_div_scale_f32 v38, vcc, 1.0, v0, 1.0
	v_lshlrev_b64 v[34:35], 11, v[122:123]
	v_fma_f32 v39, -v36, v37, 1.0
	v_fmac_f32_e32 v37, v39, v37
	v_mul_f32_e32 v39, v38, v37
	v_fma_f32 v40, -v36, v39, v38
	v_fmac_f32_e32 v39, v40, v37
	v_fma_f32 v36, -v36, v39, v38
	v_div_fmas_f32 v36, v36, v37, v39
	v_div_fixup_f32 v36, v36, v0, 1.0
	v_pk_mul_f32 v[18:19], v[18:19], v[36:37] op_sel_hi:[1,0]
	v_pk_mul_f32 v[20:21], v[20:21], v[36:37] op_sel_hi:[1,0]
	v_mov_b32_e32 v0, v21
	v_mov_b32_e32 v21, v19
	v_cvt_pk_bf16_f32 v19, v20, v0
	v_cvt_pk_bf16_f32 v18, v18, v21
	v_lshl_add_u64 v[20:21], v[118:119], 0, v[34:35]
	v_lshlrev_b32_e32 v0, 1, v134
	v_lshl_add_u64 v[20:21], v[20:21], 0, v[0:1]
	global_store_dwordx2 v[20:21], v[18:19], off
	v_pk_mul_f32 v[18:19], v[22:23], v[36:37] op_sel_hi:[1,0]
	v_pk_mul_f32 v[22:23], v[24:25], v[36:37] op_sel_hi:[1,0]
	v_mov_b32_e32 v24, v19
	v_cvt_pk_bf16_f32 v19, v22, v23
	v_cvt_pk_bf16_f32 v18, v18, v24
	v_pk_mul_f32 v[10:11], v[10:11], v[36:37] op_sel_hi:[1,0]
	v_pk_mul_f32 v[12:13], v[12:13], v[36:37] op_sel_hi:[1,0]
	global_store_dwordx2 v[20:21], v[18:19], off offset:32
	v_mov_b32_e32 v18, v11
	v_cvt_pk_bf16_f32 v11, v12, v13
	v_cvt_pk_bf16_f32 v10, v10, v18
	global_store_dwordx2 v[20:21], v[10:11], off offset:64
	v_mov_b32_e32 v10, v60
	s_nop 1
	v_permlane16_swap_b32_e32 v10, v60
	v_pk_mul_f32 v[4:5], v[4:5], v[36:37] op_sel_hi:[1,0]
	v_pk_mul_f32 v[2:3], v[2:3], v[36:37] op_sel_hi:[1,0]
	v_add_f32_e32 v10, v60, v10
	v_mov_b32_e32 v19, v10
	s_nop 1
	v_permlane32_swap_b32_e32 v19, v10
	v_mov_b32_e32 v11, v3
	v_add_f32_e32 v10, v10, v19
	v_div_scale_f32 v12, s[2:3], v10, v10, 1.0
	v_rcp_f32_e32 v13, v12
	v_cvt_pk_bf16_f32 v3, v4, v5
	v_cvt_pk_bf16_f32 v2, v2, v11
	global_store_dwordx2 v[20:21], v[2:3], off offset:96
	v_fma_f32 v2, -v12, v13, 1.0
	v_fmac_f32_e32 v13, v2, v13
	v_div_scale_f32 v2, vcc, 1.0, v10, 1.0
	v_mul_f32_e32 v3, v2, v13
	v_fma_f32 v4, -v12, v3, v2
	v_fmac_f32_e32 v3, v4, v13
	v_fma_f32 v2, -v12, v3, v2
	v_div_fmas_f32 v2, v2, v13, v3
	v_div_fixup_f32 v2, v2, v10, 1.0
	v_pk_mul_f32 v[10:11], v[30:31], v[2:3] op_sel_hi:[1,0]
	v_pk_mul_f32 v[12:13], v[32:33], v[2:3] op_sel_hi:[1,0]
	v_lshlrev_b64 v[4:5], 11, v[120:121]
	v_bfe_u32 v3, v13, 16, 1
	v_bfe_u32 v18, v12, 16, 1
	v_add3_u32 v12, v12, v18, s0
	v_add3_u32 v3, v13, v3, s0
	v_mov_b32_e32 v13, v11
	v_lshl_add_u64 v[4:5], v[118:119], 0, v[4:5]
	v_perm_b32 v11, v3, v12, s19
	v_cvt_pk_bf16_f32 v10, v10, v13
	v_lshl_add_u64 v[4:5], v[4:5], 0, v[0:1]
	global_store_dwordx2 v[4:5], v[10:11], off
	v_pk_mul_f32 v[10:11], v[26:27], v[2:3] op_sel_hi:[1,0]
	v_pk_mul_f32 v[12:13], v[28:29], v[2:3] op_sel_hi:[1,0]
	v_bfe_u32 v0, v13, 16, 1
	v_bfe_u32 v3, v12, 16, 1
	v_add3_u32 v3, v12, v3, s0
	v_add3_u32 v0, v13, v0, s0
	v_mov_b32_e32 v12, v11
	v_perm_b32 v11, v0, v3, s19
	v_cvt_pk_bf16_f32 v10, v10, v12
	global_store_dwordx2 v[4:5], v[10:11], off offset:32
	v_pk_mul_f32 v[10:11], v[14:15], v[2:3] op_sel_hi:[1,0]
	v_pk_mul_f32 v[12:13], v[16:17], v[2:3] op_sel_hi:[1,0]
	v_bfe_u32 v0, v13, 16, 1
	v_bfe_u32 v3, v12, 16, 1
	v_add3_u32 v3, v12, v3, s0
	v_add3_u32 v0, v13, v0, s0
	v_mov_b32_e32 v12, v11
	v_perm_b32 v11, v0, v3, s19
	v_cvt_pk_bf16_f32 v10, v10, v12
	v_pk_mul_f32 v[6:7], v[6:7], v[2:3] op_sel_hi:[1,0]
	v_pk_mul_f32 v[2:3], v[8:9], v[2:3] op_sel_hi:[1,0]
	global_store_dwordx2 v[4:5], v[10:11], off offset:64
	v_cvt_pk_bf16_f32 v3, v2, v3
	v_cvt_pk_bf16_f32 v2, v6, v7
	global_store_dwordx2 v[4:5], v[2:3], off offset:96
	s_cbranch_scc1 .LBB0_423

.LBB0_423:
	s_setprio 0
	s_mov_b64 s[2:3], 0
